# speedup vs baseline: 1.0005x; 1.0005x over previous
; __device__ void attn_phase(const u16* q, const u16* k, const u16* vt, u16* mix, int tid) {
;   const int wv = tid >> 6;
;   const int gw = blockIdx.x * 8 + wv, nw = gridDim.x * 8;
;   for (int it = gw; it < 64 * 128; it += nw) {
;     int bh = it >> 7, qt = it & 127;
;     attn_item(q, k, vt, mix, bh, qt, tid);
.LBB0_70:
	s_and_b64 vcc, exec, s[0:1]
	s_cbranch_vccz .LBB0_212
	s_cmp_gt_i32 s77, 1
	s_mov_b64 s[0:1], -1
	s_cbranch_scc0 .LBB0_210
	s_cmp_gt_i32 s77, 2
	s_cbranch_scc0 .LBB0_190
	s_add_u32 s0, s79, 0x10000000
	s_addc_u32 s1, s76, 0
	s_add_u32 s72, s79, 0x12000000
	v_writelane_b32 v226, s0, 16
	s_addc_u32 s73, s76, 0
	s_nop 0
	v_writelane_b32 v226, s1, 17
	s_add_u32 s0, s79, 0x14000000
	s_addc_u32 s1, s76, 0
	v_writelane_b32 v226, s0, 18
	s_cmp_gt_i32 s77, 3
	s_nop 0
	v_writelane_b32 v226, s1, 19
	s_mov_b64 s[0:1], -1
	s_cbranch_scc0 .LBB0_101
	v_readfirstlane_b32 s0, v164
	s_lshr_b32 s0, s0, 8
	s_cmp_eq_u32 s0, 1
	s_cbranch_scc0 .Lstag_attn
	s_sleep 18
